# XCD-aware item order in NA / SWA / conv phases (items sharing staged rows go to workgroups of one XCD)
# baseline (speedup 1.0000x reference)
.LBB0_480:
	s_and_b32 s98, s0, 0xffffff00
	s_and_b32 s99, s0, 7
	s_lshl_b32 s99, s99, 5
	s_or_b32 s98, s98, s99
	s_bfe_u32 s99, s0, 0x50003
	s_or_b32 s98, s98, s99
	s_sub_i32 s99, s98, s0
	s_lshl_b32 s99, s99, 6
	v_lshl_add_u32 v8, s98, 6, v56
	s_mov_b32 s2, 0x10000
	v_cmp_gt_i32_e64 s[2:3], s2, v8
	v_mov_b32_e32 v14, 0
	v_mov_b32_e32 v15, 0
	v_cndmask_b32_e64 v9, v227, v252, s[2:3]
	v_and_b32_e32 v9, v9, v8
	v_add_u32_e32 v84, -15, v9
	v_cndmask_b32_e64 v83, v223, v230, s[2:3]
	v_sub_u32_e32 v82, v8, v9
	v_add_u32_e32 v206, v84, v57
	v_cmp_lt_u32_e64 s[2:3], v206, v83
	s_and_saveexec_b64 s[4:5], s[2:3]
	v_add_u32_e32 v8, v206, v82
	v_ashrrev_i32_e32 v9, 31, v8
	v_lshlrev_b64 v[8:9], 9, v[8:9]
	v_lshl_add_u64 v[10:11], v[18:19], 0, v[8:9]
	v_lshl_add_u64 v[12:13], v[20:21], 0, v[8:9]
	global_load_dwordx4 v[148:151], v[10:11], off
	global_load_dwordx4 v[152:155], v[12:13], off
	s_mov_b64 exec, s[4:5]
	v_add_u32_e32 v206, v84, v65
	v_cmp_lt_u32_e64 s[2:3], v206, v83
	s_and_saveexec_b64 s[4:5], s[2:3]
	v_add_u32_e32 v8, v206, v82
	v_ashrrev_i32_e32 v9, 31, v8
	v_lshlrev_b64 v[8:9], 9, v[8:9]
	v_lshl_add_u64 v[10:11], v[18:19], 0, v[8:9]
	v_lshl_add_u64 v[12:13], v[20:21], 0, v[8:9]
	global_load_dwordx4 v[156:159], v[10:11], off
	global_load_dwordx4 v[160:163], v[12:13], off
	s_mov_b64 exec, s[4:5]
	v_add_u32_e32 v206, v84, v66
	v_cmp_lt_u32_e64 s[2:3], v206, v83
	s_and_saveexec_b64 s[4:5], s[2:3]
	v_add_u32_e32 v8, v206, v82
	v_ashrrev_i32_e32 v9, 31, v8
	v_lshlrev_b64 v[8:9], 9, v[8:9]
	v_lshl_add_u64 v[10:11], v[18:19], 0, v[8:9]
	v_lshl_add_u64 v[12:13], v[20:21], 0, v[8:9]
	global_load_dwordx4 v[164:167], v[10:11], off
	global_load_dwordx4 v[168:171], v[12:13], off
	s_mov_b64 exec, s[4:5]
	v_add_u32_e32 v206, v84, v67
	v_cmp_lt_u32_e64 s[2:3], v206, v83
	s_and_saveexec_b64 s[4:5], s[2:3]
	v_add_u32_e32 v8, v206, v82
	v_ashrrev_i32_e32 v9, 31, v8
	v_lshlrev_b64 v[8:9], 9, v[8:9]
	v_lshl_add_u64 v[10:11], v[18:19], 0, v[8:9]
	v_lshl_add_u64 v[12:13], v[20:21], 0, v[8:9]
	global_load_dwordx4 v[172:175], v[10:11], off
	global_load_dwordx4 v[176:179], v[12:13], off
	s_mov_b64 exec, s[4:5]
	v_add_u32_e32 v206, v84, v68
	v_cmp_lt_u32_e64 s[2:3], v206, v83
	s_and_saveexec_b64 s[4:5], s[2:3]
	v_add_u32_e32 v8, v206, v82
	v_ashrrev_i32_e32 v9, 31, v8
	v_lshlrev_b64 v[8:9], 9, v[8:9]
	v_lshl_add_u64 v[10:11], v[18:19], 0, v[8:9]
	v_lshl_add_u64 v[12:13], v[20:21], 0, v[8:9]
	global_load_dwordx4 v[180:183], v[10:11], off
	global_load_dwordx4 v[184:187], v[12:13], off
	s_mov_b64 exec, s[4:5]
	v_add_u32_e32 v206, v84, v69
	v_cmp_lt_u32_e64 s[2:3], v206, v83
	s_and_saveexec_b64 s[4:5], s[2:3]
	v_add_u32_e32 v8, v206, v82
	v_ashrrev_i32_e32 v9, 31, v8
	v_lshlrev_b64 v[8:9], 9, v[8:9]
	v_lshl_add_u64 v[10:11], v[18:19], 0, v[8:9]
	v_lshl_add_u64 v[12:13], v[20:21], 0, v[8:9]
	global_load_dwordx4 v[188:191], v[10:11], off
	global_load_dwordx4 v[208:211], v[12:13], off
	s_mov_b64 exec, s[4:5]
	v_add_u32_e32 v206, v84, v70
	v_cmp_lt_u32_e64 s[2:3], v206, v83
	s_and_saveexec_b64 s[4:5], s[2:3]
	v_add_u32_e32 v8, v206, v82
	v_ashrrev_i32_e32 v9, 31, v8
	v_lshlrev_b64 v[8:9], 9, v[8:9]
	v_lshl_add_u64 v[10:11], v[18:19], 0, v[8:9]
	v_lshl_add_u64 v[12:13], v[20:21], 0, v[8:9]
	global_load_dwordx4 v[212:215], v[10:11], off
	global_load_dwordx4 v[216:219], v[12:13], off
	s_mov_b64 exec, s[4:5]
	v_add_u32_e32 v206, v84, v71
	v_cmp_lt_u32_e64 s[2:3], v206, v83
	s_and_b64 s[2:3], s[2:3], vcc
	s_and_saveexec_b64 s[4:5], s[2:3]
	v_add_u32_e32 v8, v206, v82
	v_ashrrev_i32_e32 v9, 31, v8
	v_lshlrev_b64 v[8:9], 9, v[8:9]
	v_lshl_add_u64 v[10:11], v[18:19], 0, v[8:9]
	v_lshl_add_u64 v[12:13], v[20:21], 0, v[8:9]
	global_load_dwordx4 v[244:247], v[10:11], off
	global_load_dwordx4 v[248:251], v[12:13], off
	s_mov_b64 exec, s[4:5]
	s_waitcnt vmcnt(0)
	v_mov_b64_e32 v[8:9], 0
	v_mov_b64_e32 v[10:11], 0
	v_mov_b64_e32 v[12:13], 0
	v_mov_b64_e32 v[14:15], 0
	v_add_u32_e32 v206, v84, v57
	v_cmp_lt_u32_e64 s[2:3], v206, v83
	s_and_saveexec_b64 s[4:5], s[2:3]
	v_lshlrev_b32_e32 v16, 16, v148
	v_and_b32_e32 v17, 0xffff0000, v148
	v_lshlrev_b32_e32 v146, 16, v152
	v_and_b32_e32 v147, 0xffff0000, v152
	v_pk_mul_f32 v[8:9], v[16:17], v[146:147]
	v_lshlrev_b32_e32 v16, 16, v149
	v_and_b32_e32 v17, 0xffff0000, v149
	v_lshlrev_b32_e32 v146, 16, v153
	v_and_b32_e32 v147, 0xffff0000, v153
	v_pk_mul_f32 v[10:11], v[16:17], v[146:147]
	v_lshlrev_b32_e32 v16, 16, v150
	v_and_b32_e32 v17, 0xffff0000, v150
	v_lshlrev_b32_e32 v146, 16, v154
	v_and_b32_e32 v147, 0xffff0000, v154
	v_pk_mul_f32 v[12:13], v[16:17], v[146:147]
	v_lshlrev_b32_e32 v16, 16, v151
	v_and_b32_e32 v17, 0xffff0000, v151
	v_lshlrev_b32_e32 v146, 16, v155
	v_and_b32_e32 v147, 0xffff0000, v155
	v_pk_mul_f32 v[14:15], v[16:17], v[146:147]
	s_mov_b64 exec, s[4:5]
	ds_write_b128 v74, v[8:11]
	ds_write_b128 v74, v[12:15] offset:16
	v_mov_b64_e32 v[86:87], 0
	v_mov_b64_e32 v[88:89], 0
	v_mov_b64_e32 v[90:91], 0
	v_mov_b64_e32 v[92:93], 0
	v_add_u32_e32 v206, v84, v65
	v_cmp_lt_u32_e64 s[2:3], v206, v83
	s_and_saveexec_b64 s[4:5], s[2:3]
	v_lshlrev_b32_e32 v16, 16, v156
	v_and_b32_e32 v17, 0xffff0000, v156
	v_lshlrev_b32_e32 v146, 16, v160
	v_and_b32_e32 v147, 0xffff0000, v160
	v_pk_mul_f32 v[86:87], v[16:17], v[146:147]
	v_lshlrev_b32_e32 v16, 16, v157
	v_and_b32_e32 v17, 0xffff0000, v157
	v_lshlrev_b32_e32 v146, 16, v161
	v_and_b32_e32 v147, 0xffff0000, v161
	v_pk_mul_f32 v[88:89], v[16:17], v[146:147]
	v_lshlrev_b32_e32 v16, 16, v158
	v_and_b32_e32 v17, 0xffff0000, v158
	v_lshlrev_b32_e32 v146, 16, v162
	v_and_b32_e32 v147, 0xffff0000, v162
	v_pk_mul_f32 v[90:91], v[16:17], v[146:147]
	v_lshlrev_b32_e32 v16, 16, v159
	v_and_b32_e32 v17, 0xffff0000, v159
	v_lshlrev_b32_e32 v146, 16, v163
	v_and_b32_e32 v147, 0xffff0000, v163
	v_pk_mul_f32 v[92:93], v[16:17], v[146:147]
	s_mov_b64 exec, s[4:5]
	ds_write_b128 v75, v[86:89]
	ds_write_b128 v75, v[90:93] offset:16
	v_mov_b64_e32 v[8:9], 0
	v_mov_b64_e32 v[10:11], 0
	v_mov_b64_e32 v[12:13], 0
	v_mov_b64_e32 v[14:15], 0
	v_add_u32_e32 v206, v84, v66
	v_cmp_lt_u32_e64 s[2:3], v206, v83
	s_and_saveexec_b64 s[4:5], s[2:3]
	v_lshlrev_b32_e32 v16, 16, v164
	v_and_b32_e32 v17, 0xffff0000, v164
	v_lshlrev_b32_e32 v146, 16, v168
	v_and_b32_e32 v147, 0xffff0000, v168
	v_pk_mul_f32 v[8:9], v[16:17], v[146:147]
	v_lshlrev_b32_e32 v16, 16, v165
	v_and_b32_e32 v17, 0xffff0000, v165
	v_lshlrev_b32_e32 v146, 16, v169
	v_and_b32_e32 v147, 0xffff0000, v169
	v_pk_mul_f32 v[10:11], v[16:17], v[146:147]
	v_lshlrev_b32_e32 v16, 16, v166
	v_and_b32_e32 v17, 0xffff0000, v166
	v_lshlrev_b32_e32 v146, 16, v170
	v_and_b32_e32 v147, 0xffff0000, v170
	v_pk_mul_f32 v[12:13], v[16:17], v[146:147]
	v_lshlrev_b32_e32 v16, 16, v167
	v_and_b32_e32 v17, 0xffff0000, v167
	v_lshlrev_b32_e32 v146, 16, v171
	v_and_b32_e32 v147, 0xffff0000, v171
	v_pk_mul_f32 v[14:15], v[16:17], v[146:147]
	s_mov_b64 exec, s[4:5]
	ds_write_b128 v76, v[8:11]
	ds_write_b128 v76, v[12:15] offset:16
	v_mov_b64_e32 v[86:87], 0
	v_mov_b64_e32 v[88:89], 0
	v_mov_b64_e32 v[90:91], 0
	v_mov_b64_e32 v[92:93], 0
	v_add_u32_e32 v206, v84, v67
	v_cmp_lt_u32_e64 s[2:3], v206, v83
	s_and_saveexec_b64 s[4:5], s[2:3]
	v_lshlrev_b32_e32 v16, 16, v172
	v_and_b32_e32 v17, 0xffff0000, v172
	v_lshlrev_b32_e32 v146, 16, v176
	v_and_b32_e32 v147, 0xffff0000, v176
	v_pk_mul_f32 v[86:87], v[16:17], v[146:147]
	v_lshlrev_b32_e32 v16, 16, v173
	v_and_b32_e32 v17, 0xffff0000, v173
	v_lshlrev_b32_e32 v146, 16, v177
	v_and_b32_e32 v147, 0xffff0000, v177
	v_pk_mul_f32 v[88:89], v[16:17], v[146:147]
	v_lshlrev_b32_e32 v16, 16, v174
	v_and_b32_e32 v17, 0xffff0000, v174
	v_lshlrev_b32_e32 v146, 16, v178
	v_and_b32_e32 v147, 0xffff0000, v178
	v_pk_mul_f32 v[90:91], v[16:17], v[146:147]
	v_lshlrev_b32_e32 v16, 16, v175
	v_and_b32_e32 v17, 0xffff0000, v175
	v_lshlrev_b32_e32 v146, 16, v179
	v_and_b32_e32 v147, 0xffff0000, v179
	v_pk_mul_f32 v[92:93], v[16:17], v[146:147]
	s_mov_b64 exec, s[4:5]
	ds_write_b128 v77, v[86:89]
	ds_write_b128 v77, v[90:93] offset:16
	v_mov_b64_e32 v[8:9], 0
	v_mov_b64_e32 v[10:11], 0
	v_mov_b64_e32 v[12:13], 0
	v_mov_b64_e32 v[14:15], 0
	v_add_u32_e32 v206, v84, v68
	v_cmp_lt_u32_e64 s[2:3], v206, v83
	s_and_saveexec_b64 s[4:5], s[2:3]
	v_lshlrev_b32_e32 v16, 16, v180
	v_and_b32_e32 v17, 0xffff0000, v180
	v_lshlrev_b32_e32 v146, 16, v184
	v_and_b32_e32 v147, 0xffff0000, v184
	v_pk_mul_f32 v[8:9], v[16:17], v[146:147]
	v_lshlrev_b32_e32 v16, 16, v181
	v_and_b32_e32 v17, 0xffff0000, v181
	v_lshlrev_b32_e32 v146, 16, v185
	v_and_b32_e32 v147, 0xffff0000, v185
	v_pk_mul_f32 v[10:11], v[16:17], v[146:147]
	v_lshlrev_b32_e32 v16, 16, v182
	v_and_b32_e32 v17, 0xffff0000, v182
	v_lshlrev_b32_e32 v146, 16, v186
	v_and_b32_e32 v147, 0xffff0000, v186
	v_pk_mul_f32 v[12:13], v[16:17], v[146:147]
	v_lshlrev_b32_e32 v16, 16, v183
	v_and_b32_e32 v17, 0xffff0000, v183
	v_lshlrev_b32_e32 v146, 16, v187
	v_and_b32_e32 v147, 0xffff0000, v187
	v_pk_mul_f32 v[14:15], v[16:17], v[146:147]
	s_mov_b64 exec, s[4:5]
	ds_write_b128 v78, v[8:11]
	ds_write_b128 v78, v[12:15] offset:16
	v_mov_b64_e32 v[86:87], 0
	v_mov_b64_e32 v[88:89], 0
	v_mov_b64_e32 v[90:91], 0
	v_mov_b64_e32 v[92:93], 0
	v_add_u32_e32 v206, v84, v69
	v_cmp_lt_u32_e64 s[2:3], v206, v83
	s_and_saveexec_b64 s[4:5], s[2:3]
	v_lshlrev_b32_e32 v16, 16, v188
	v_and_b32_e32 v17, 0xffff0000, v188
	v_lshlrev_b32_e32 v146, 16, v208
	v_and_b32_e32 v147, 0xffff0000, v208
	v_pk_mul_f32 v[86:87], v[16:17], v[146:147]
	v_lshlrev_b32_e32 v16, 16, v189
	v_and_b32_e32 v17, 0xffff0000, v189
	v_lshlrev_b32_e32 v146, 16, v209
	v_and_b32_e32 v147, 0xffff0000, v209
	v_pk_mul_f32 v[88:89], v[16:17], v[146:147]
	v_lshlrev_b32_e32 v16, 16, v190
	v_and_b32_e32 v17, 0xffff0000, v190
	v_lshlrev_b32_e32 v146, 16, v210
	v_and_b32_e32 v147, 0xffff0000, v210
	v_pk_mul_f32 v[90:91], v[16:17], v[146:147]
	v_lshlrev_b32_e32 v16, 16, v191
	v_and_b32_e32 v17, 0xffff0000, v191
	v_lshlrev_b32_e32 v146, 16, v211
	v_and_b32_e32 v147, 0xffff0000, v211
	v_pk_mul_f32 v[92:93], v[16:17], v[146:147]
	s_mov_b64 exec, s[4:5]
	ds_write_b128 v79, v[86:89]
	ds_write_b128 v79, v[90:93] offset:16
	v_mov_b64_e32 v[8:9], 0
	v_mov_b64_e32 v[10:11], 0
	v_mov_b64_e32 v[12:13], 0
	v_mov_b64_e32 v[14:15], 0
	v_add_u32_e32 v206, v84, v70
	v_cmp_lt_u32_e64 s[2:3], v206, v83
	s_and_saveexec_b64 s[4:5], s[2:3]
	v_lshlrev_b32_e32 v16, 16, v212
	v_and_b32_e32 v17, 0xffff0000, v212
	v_lshlrev_b32_e32 v146, 16, v216
	v_and_b32_e32 v147, 0xffff0000, v216
	v_pk_mul_f32 v[8:9], v[16:17], v[146:147]
	v_lshlrev_b32_e32 v16, 16, v213
	v_and_b32_e32 v17, 0xffff0000, v213
	v_lshlrev_b32_e32 v146, 16, v217
	v_and_b32_e32 v147, 0xffff0000, v217
	v_pk_mul_f32 v[10:11], v[16:17], v[146:147]
	v_lshlrev_b32_e32 v16, 16, v214
	v_and_b32_e32 v17, 0xffff0000, v214
	v_lshlrev_b32_e32 v146, 16, v218
	v_and_b32_e32 v147, 0xffff0000, v218
	v_pk_mul_f32 v[12:13], v[16:17], v[146:147]
	v_lshlrev_b32_e32 v16, 16, v215
	v_and_b32_e32 v17, 0xffff0000, v215
	v_lshlrev_b32_e32 v146, 16, v219
	v_and_b32_e32 v147, 0xffff0000, v219
	v_pk_mul_f32 v[14:15], v[16:17], v[146:147]
	s_mov_b64 exec, s[4:5]
	ds_write_b128 v80, v[8:11]
	ds_write_b128 v80, v[12:15] offset:16
	s_and_saveexec_b64 s[6:7], vcc
	v_mov_b64_e32 v[86:87], 0
	v_mov_b64_e32 v[88:89], 0
	v_mov_b64_e32 v[90:91], 0
	v_mov_b64_e32 v[92:93], 0
	v_add_u32_e32 v206, v84, v71
	v_cmp_lt_u32_e64 s[2:3], v206, v83
	s_and_saveexec_b64 s[4:5], s[2:3]
	v_lshlrev_b32_e32 v16, 16, v244
	v_and_b32_e32 v17, 0xffff0000, v244
	v_lshlrev_b32_e32 v146, 16, v248
	v_and_b32_e32 v147, 0xffff0000, v248
	v_pk_mul_f32 v[86:87], v[16:17], v[146:147]
	v_lshlrev_b32_e32 v16, 16, v245
	v_and_b32_e32 v17, 0xffff0000, v245
	v_lshlrev_b32_e32 v146, 16, v249
	v_and_b32_e32 v147, 0xffff0000, v249
	v_pk_mul_f32 v[88:89], v[16:17], v[146:147]
	v_lshlrev_b32_e32 v16, 16, v246
	v_and_b32_e32 v17, 0xffff0000, v246
	v_lshlrev_b32_e32 v146, 16, v250
	v_and_b32_e32 v147, 0xffff0000, v250
	v_pk_mul_f32 v[90:91], v[16:17], v[146:147]
	v_lshlrev_b32_e32 v16, 16, v247
	v_and_b32_e32 v17, 0xffff0000, v247
	v_lshlrev_b32_e32 v146, 16, v251
	v_and_b32_e32 v147, 0xffff0000, v251
	v_pk_mul_f32 v[92:93], v[16:17], v[146:147]
	s_mov_b64 exec, s[4:5]
	ds_write_b128 v81, v[86:89]
	ds_write_b128 v81, v[90:93] offset:16
	s_mov_b64 exec, s[6:7]
	s_waitcnt lgkmcnt(0)
	s_barrier
	ds_read2st64_b32 v[8:9], v58 offset1:4
	ds_read2st64_b32 v[10:11], v58 offset0:8 offset1:12
	ds_read2st64_b32 v[12:13], v58 offset0:16 offset1:20
	ds_read2st64_b32 v[14:15], v58 offset0:24 offset1:28
	ds_read2st64_b32 v[16:17], v58 offset0:32 offset1:36
	s_waitcnt vmcnt(2) lgkmcnt(4)
	v_fma_f32 v8, v8, v24, v55
	v_fmac_f32_e32 v8, v9, v25
	v_fma_f32 v9, v9, v24, v55
	s_waitcnt lgkmcnt(3)
	v_fmac_f32_e32 v8, v10, v26
	v_fmac_f32_e32 v9, v10, v25
	v_fma_f32 v10, v10, v24, v55
	v_fmac_f32_e32 v8, v11, v27
	v_fmac_f32_e32 v9, v11, v26
	v_fmac_f32_e32 v10, v11, v25
	v_fma_f32 v11, v11, v24, v55
	s_waitcnt lgkmcnt(2)
	v_fmac_f32_e32 v8, v12, v28
	v_fmac_f32_e32 v9, v12, v27
	v_fmac_f32_e32 v10, v12, v26
	v_fmac_f32_e32 v11, v12, v25
	v_fma_f32 v12, v12, v24, v55
	v_fmac_f32_e32 v8, v13, v29
	v_fmac_f32_e32 v9, v13, v28
	v_fmac_f32_e32 v10, v13, v27
	v_fmac_f32_e32 v11, v13, v26
	v_fmac_f32_e32 v12, v13, v25
	v_fma_f32 v13, v13, v24, v55
	ds_read2st64_b32 v[82:83], v58 offset0:40 offset1:44
	s_waitcnt lgkmcnt(2)
	v_fmac_f32_e32 v8, v14, v30
	v_fmac_f32_e32 v9, v14, v29
	v_fmac_f32_e32 v10, v14, v28
	v_fmac_f32_e32 v11, v14, v27
	v_fmac_f32_e32 v12, v14, v26
	v_fmac_f32_e32 v13, v14, v25
	v_fma_f32 v14, v14, v24, v55
	v_fmac_f32_e32 v8, v15, v31
	v_fmac_f32_e32 v9, v15, v30
	v_fmac_f32_e32 v10, v15, v29
	v_fmac_f32_e32 v11, v15, v28
	v_fmac_f32_e32 v12, v15, v27
	v_fmac_f32_e32 v13, v15, v26
	v_fmac_f32_e32 v14, v15, v25
	v_fma_f32 v15, v15, v24, v55
	ds_read2st64_b32 v[84:85], v58 offset0:48 offset1:52
	s_waitcnt lgkmcnt(2)
	v_fmac_f32_e32 v8, v16, v32
	v_fmac_f32_e32 v9, v16, v31
	v_fmac_f32_e32 v10, v16, v30
	v_fmac_f32_e32 v11, v16, v29
	v_fmac_f32_e32 v12, v16, v28
	v_fmac_f32_e32 v13, v16, v27
	v_fmac_f32_e32 v14, v16, v26
	v_fmac_f32_e32 v15, v16, v25
	v_fma_f32 v16, v16, v24, v55
	v_fmac_f32_e32 v8, v17, v33
	v_fmac_f32_e32 v9, v17, v32
	v_fmac_f32_e32 v10, v17, v31
	v_fmac_f32_e32 v11, v17, v30
	v_fmac_f32_e32 v12, v17, v29
	v_fmac_f32_e32 v13, v17, v28
	v_fmac_f32_e32 v14, v17, v27
	v_fmac_f32_e32 v15, v17, v26
	v_fmac_f32_e32 v16, v17, v25
	v_fma_f32 v17, v17, v24, v55
	ds_read2st64_b32 v[86:87], v58 offset0:56 offset1:60
	s_waitcnt lgkmcnt(2)
	v_fmac_f32_e32 v8, v82, v34
	v_fmac_f32_e32 v9, v82, v33
	v_fmac_f32_e32 v10, v82, v32
	v_fmac_f32_e32 v11, v82, v31
	v_fmac_f32_e32 v12, v82, v30
	v_fmac_f32_e32 v13, v82, v29
	v_fmac_f32_e32 v14, v82, v28
	v_fmac_f32_e32 v15, v82, v27
	v_fmac_f32_e32 v16, v82, v26
	v_fmac_f32_e32 v17, v82, v25
	v_fma_f32 v82, v82, v24, v55
	v_fmac_f32_e32 v8, v83, v35
	v_fmac_f32_e32 v9, v83, v34
	v_fmac_f32_e32 v10, v83, v33
	v_fmac_f32_e32 v11, v83, v32
	v_fmac_f32_e32 v12, v83, v31
	v_fmac_f32_e32 v13, v83, v30
	v_fmac_f32_e32 v14, v83, v29
	v_fmac_f32_e32 v15, v83, v28
	v_fmac_f32_e32 v16, v83, v27
	v_fmac_f32_e32 v17, v83, v26
	v_fmac_f32_e32 v82, v83, v25
	v_fma_f32 v83, v83, v24, v55
	ds_read2st64_b32 v[88:89], v58 offset0:64 offset1:68
	s_waitcnt lgkmcnt(2)
	v_fmac_f32_e32 v8, v84, v36
	v_fmac_f32_e32 v9, v84, v35
	v_fmac_f32_e32 v10, v84, v34
	v_fmac_f32_e32 v11, v84, v33
	v_fmac_f32_e32 v12, v84, v32
	v_fmac_f32_e32 v13, v84, v31
	v_fmac_f32_e32 v14, v84, v30
	v_fmac_f32_e32 v15, v84, v29
	v_fmac_f32_e32 v16, v84, v28
	v_fmac_f32_e32 v17, v84, v27
	v_fmac_f32_e32 v82, v84, v26
	v_fmac_f32_e32 v83, v84, v25
	v_fma_f32 v84, v84, v24, v55
	v_fmac_f32_e32 v8, v85, v37
	v_fmac_f32_e32 v9, v85, v36
	v_fmac_f32_e32 v10, v85, v35
	v_fmac_f32_e32 v11, v85, v34
	v_fmac_f32_e32 v12, v85, v33
	v_fmac_f32_e32 v13, v85, v32
	v_fmac_f32_e32 v14, v85, v31
	v_fmac_f32_e32 v15, v85, v30
	v_fmac_f32_e32 v16, v85, v29
	v_fmac_f32_e32 v17, v85, v28
	v_fmac_f32_e32 v82, v85, v27
	v_fmac_f32_e32 v83, v85, v26
	v_fmac_f32_e32 v84, v85, v25
	v_fma_f32 v85, v85, v24, v55
	ds_read2st64_b32 v[90:91], v58 offset0:72 offset1:76
	s_waitcnt lgkmcnt(2)
	v_fmac_f32_e32 v8, v86, v38
	v_fmac_f32_e32 v9, v86, v37
	v_fmac_f32_e32 v10, v86, v36
	v_fmac_f32_e32 v11, v86, v35
	v_fmac_f32_e32 v12, v86, v34
	v_fmac_f32_e32 v13, v86, v33
	v_fmac_f32_e32 v14, v86, v32
	v_fmac_f32_e32 v15, v86, v31
	v_fmac_f32_e32 v16, v86, v30
	v_fmac_f32_e32 v17, v86, v29
	v_fmac_f32_e32 v82, v86, v28
	v_fmac_f32_e32 v83, v86, v27
	v_fmac_f32_e32 v84, v86, v26
	v_fmac_f32_e32 v85, v86, v25
	v_fma_f32 v86, v86, v24, v55
	v_fmac_f32_e32 v8, v87, v39
	v_fmac_f32_e32 v9, v87, v38
	v_fmac_f32_e32 v10, v87, v37
	v_fmac_f32_e32 v11, v87, v36
	v_fmac_f32_e32 v12, v87, v35
	v_fmac_f32_e32 v13, v87, v34
	v_fmac_f32_e32 v14, v87, v33
	v_fmac_f32_e32 v15, v87, v32
	v_fmac_f32_e32 v16, v87, v31
	v_fmac_f32_e32 v17, v87, v30
	v_fmac_f32_e32 v82, v87, v29
	v_fmac_f32_e32 v83, v87, v28
	v_fmac_f32_e32 v84, v87, v27
	v_fmac_f32_e32 v85, v87, v26
	v_fmac_f32_e32 v86, v87, v25
	v_fma_f32 v87, v87, v24, v55
	ds_read2st64_b32 v[92:93], v58 offset0:80 offset1:84
	s_waitcnt lgkmcnt(2)
	v_fmac_f32_e32 v8, v88, v40
	v_fmac_f32_e32 v9, v88, v39
	v_fmac_f32_e32 v10, v88, v38
	v_fmac_f32_e32 v11, v88, v37
	v_fmac_f32_e32 v12, v88, v36
	v_fmac_f32_e32 v13, v88, v35
	v_fmac_f32_e32 v14, v88, v34
	v_fmac_f32_e32 v15, v88, v33
	v_fmac_f32_e32 v16, v88, v32
	v_fmac_f32_e32 v17, v88, v31
	v_fmac_f32_e32 v82, v88, v30
	v_fmac_f32_e32 v83, v88, v29
	v_fmac_f32_e32 v84, v88, v28
	v_fmac_f32_e32 v85, v88, v27
	v_fmac_f32_e32 v86, v88, v26
	v_fmac_f32_e32 v87, v88, v25
	v_fma_f32 v88, v88, v24, v55
	v_fmac_f32_e32 v8, v89, v41
	v_fmac_f32_e32 v9, v89, v40
	v_fmac_f32_e32 v10, v89, v39
	v_fmac_f32_e32 v11, v89, v38
	v_fmac_f32_e32 v12, v89, v37
	v_fmac_f32_e32 v13, v89, v36
	v_fmac_f32_e32 v14, v89, v35
	v_fmac_f32_e32 v15, v89, v34
	v_fmac_f32_e32 v16, v89, v33
	v_fmac_f32_e32 v17, v89, v32
	v_fmac_f32_e32 v82, v89, v31
	v_fmac_f32_e32 v83, v89, v30
	v_fmac_f32_e32 v84, v89, v29
	v_fmac_f32_e32 v85, v89, v28
	v_fmac_f32_e32 v86, v89, v27
	v_fmac_f32_e32 v87, v89, v26
	v_fmac_f32_e32 v88, v89, v25
	v_fma_f32 v89, v89, v24, v55
	ds_read2st64_b32 v[94:95], v58 offset0:88 offset1:92
	s_waitcnt lgkmcnt(2)
	v_fmac_f32_e32 v8, v90, v42
	v_fmac_f32_e32 v9, v90, v41
	v_fmac_f32_e32 v10, v90, v40
	v_fmac_f32_e32 v11, v90, v39
	v_fmac_f32_e32 v12, v90, v38
	v_fmac_f32_e32 v13, v90, v37
	v_fmac_f32_e32 v14, v90, v36
	v_fmac_f32_e32 v15, v90, v35
	v_fmac_f32_e32 v16, v90, v34
	v_fmac_f32_e32 v17, v90, v33
	v_fmac_f32_e32 v82, v90, v32
	v_fmac_f32_e32 v83, v90, v31
	v_fmac_f32_e32 v84, v90, v30
	v_fmac_f32_e32 v85, v90, v29
	v_fmac_f32_e32 v86, v90, v28
	v_fmac_f32_e32 v87, v90, v27
	v_fmac_f32_e32 v88, v90, v26
	v_fmac_f32_e32 v89, v90, v25
	v_fma_f32 v90, v90, v24, v55
	v_fmac_f32_e32 v8, v91, v43
	v_fmac_f32_e32 v9, v91, v42
	v_fmac_f32_e32 v10, v91, v41
	v_fmac_f32_e32 v11, v91, v40
	v_fmac_f32_e32 v12, v91, v39
	v_fmac_f32_e32 v13, v91, v38
	v_fmac_f32_e32 v14, v91, v37
	v_fmac_f32_e32 v15, v91, v36
	v_fmac_f32_e32 v16, v91, v35
	v_fmac_f32_e32 v17, v91, v34
	v_fmac_f32_e32 v82, v91, v33
	v_fmac_f32_e32 v83, v91, v32
	v_fmac_f32_e32 v84, v91, v31
	v_fmac_f32_e32 v85, v91, v30
	v_fmac_f32_e32 v86, v91, v29
	v_fmac_f32_e32 v87, v91, v28
	v_fmac_f32_e32 v88, v91, v27
	v_fmac_f32_e32 v89, v91, v26
	v_fmac_f32_e32 v90, v91, v25
	v_fma_f32 v91, v91, v24, v55
	ds_read2st64_b32 v[96:97], v58 offset0:96 offset1:100
	s_waitcnt lgkmcnt(2)
	v_fmac_f32_e32 v8, v92, v44
	v_fmac_f32_e32 v9, v92, v43
	v_fmac_f32_e32 v10, v92, v42
	v_fmac_f32_e32 v11, v92, v41
	v_fmac_f32_e32 v12, v92, v40
	v_fmac_f32_e32 v13, v92, v39
	v_fmac_f32_e32 v14, v92, v38
	v_fmac_f32_e32 v15, v92, v37
	v_fmac_f32_e32 v16, v92, v36
	v_fmac_f32_e32 v17, v92, v35
	v_fmac_f32_e32 v82, v92, v34
	v_fmac_f32_e32 v83, v92, v33
	v_fmac_f32_e32 v84, v92, v32
	v_fmac_f32_e32 v85, v92, v31
	v_fmac_f32_e32 v86, v92, v30
	v_fmac_f32_e32 v87, v92, v29
	v_fmac_f32_e32 v88, v92, v28
	v_fmac_f32_e32 v89, v92, v27
	v_fmac_f32_e32 v90, v92, v26
	v_fmac_f32_e32 v91, v92, v25
	v_fma_f32 v92, v92, v24, v55
	v_fmac_f32_e32 v8, v93, v45
	v_fmac_f32_e32 v9, v93, v44
	v_fmac_f32_e32 v10, v93, v43
	v_fmac_f32_e32 v11, v93, v42
	v_fmac_f32_e32 v12, v93, v41
	v_fmac_f32_e32 v13, v93, v40
	v_fmac_f32_e32 v14, v93, v39
	v_fmac_f32_e32 v15, v93, v38
	v_fmac_f32_e32 v16, v93, v37
	v_fmac_f32_e32 v17, v93, v36
	v_fmac_f32_e32 v82, v93, v35
	v_fmac_f32_e32 v83, v93, v34
	v_fmac_f32_e32 v84, v93, v33
	v_fmac_f32_e32 v85, v93, v32
	v_fmac_f32_e32 v86, v93, v31
	v_fmac_f32_e32 v87, v93, v30
	v_fmac_f32_e32 v88, v93, v29
	v_fmac_f32_e32 v89, v93, v28
	v_fmac_f32_e32 v90, v93, v27
	v_fmac_f32_e32 v91, v93, v26
	v_fmac_f32_e32 v92, v93, v25
	v_fma_f32 v93, v93, v24, v55
	ds_read2st64_b32 v[98:99], v58 offset0:104 offset1:108
	s_waitcnt lgkmcnt(2)
	v_fmac_f32_e32 v8, v94, v46
	v_fmac_f32_e32 v9, v94, v45
	v_fmac_f32_e32 v10, v94, v44
	v_fmac_f32_e32 v11, v94, v43
	v_fmac_f32_e32 v12, v94, v42
	v_fmac_f32_e32 v13, v94, v41
	v_fmac_f32_e32 v14, v94, v40
	v_fmac_f32_e32 v15, v94, v39
	v_fmac_f32_e32 v16, v94, v38
	v_fmac_f32_e32 v17, v94, v37
	v_fmac_f32_e32 v82, v94, v36
	v_fmac_f32_e32 v83, v94, v35
	v_fmac_f32_e32 v84, v94, v34
	v_fmac_f32_e32 v85, v94, v33
	v_fmac_f32_e32 v86, v94, v32
	v_fmac_f32_e32 v87, v94, v31
	v_fmac_f32_e32 v88, v94, v30
	v_fmac_f32_e32 v89, v94, v29
	v_fmac_f32_e32 v90, v94, v28
	v_fmac_f32_e32 v91, v94, v27
	v_fmac_f32_e32 v92, v94, v26
	v_fmac_f32_e32 v93, v94, v25
	v_fma_f32 v94, v94, v24, v55
	v_fmac_f32_e32 v8, v95, v47
	v_fmac_f32_e32 v9, v95, v46
	v_fmac_f32_e32 v10, v95, v45
	v_fmac_f32_e32 v11, v95, v44
	v_fmac_f32_e32 v12, v95, v43
	v_fmac_f32_e32 v13, v95, v42
	v_fmac_f32_e32 v14, v95, v41
	v_fmac_f32_e32 v15, v95, v40
	v_fmac_f32_e32 v16, v95, v39
	v_fmac_f32_e32 v17, v95, v38
	v_fmac_f32_e32 v82, v95, v37
	v_fmac_f32_e32 v83, v95, v36
	v_fmac_f32_e32 v84, v95, v35
	v_fmac_f32_e32 v85, v95, v34
	v_fmac_f32_e32 v86, v95, v33
	v_fmac_f32_e32 v87, v95, v32
	v_fmac_f32_e32 v88, v95, v31
	v_fmac_f32_e32 v89, v95, v30
	v_fmac_f32_e32 v90, v95, v29
	v_fmac_f32_e32 v91, v95, v28
	v_fmac_f32_e32 v92, v95, v27
	v_fmac_f32_e32 v93, v95, v26
	v_fmac_f32_e32 v94, v95, v25
	v_fma_f32 v95, v95, v24, v55
	ds_read2st64_b32 v[100:101], v58 offset0:112 offset1:116
	s_waitcnt lgkmcnt(2)
	v_fmac_f32_e32 v8, v96, v48
	v_fmac_f32_e32 v9, v96, v47
	v_fmac_f32_e32 v10, v96, v46
	v_fmac_f32_e32 v11, v96, v45
	v_fmac_f32_e32 v12, v96, v44
	v_fmac_f32_e32 v13, v96, v43
	v_fmac_f32_e32 v14, v96, v42
	v_fmac_f32_e32 v15, v96, v41
	v_fmac_f32_e32 v16, v96, v40
	v_fmac_f32_e32 v17, v96, v39
	v_fmac_f32_e32 v82, v96, v38
	v_fmac_f32_e32 v83, v96, v37
	v_fmac_f32_e32 v84, v96, v36
	v_fmac_f32_e32 v85, v96, v35
	v_fmac_f32_e32 v86, v96, v34
	v_fmac_f32_e32 v87, v96, v33
	v_fmac_f32_e32 v88, v96, v32
	v_fmac_f32_e32 v89, v96, v31
	v_fmac_f32_e32 v90, v96, v30
	v_fmac_f32_e32 v91, v96, v29
	v_fmac_f32_e32 v92, v96, v28
	v_fmac_f32_e32 v93, v96, v27
	v_fmac_f32_e32 v94, v96, v26
	v_fmac_f32_e32 v95, v96, v25
	v_fma_f32 v96, v96, v24, v55
	v_fmac_f32_e32 v8, v97, v49
	v_fmac_f32_e32 v9, v97, v48
	v_fmac_f32_e32 v10, v97, v47
	v_fmac_f32_e32 v11, v97, v46
	v_fmac_f32_e32 v12, v97, v45
	v_fmac_f32_e32 v13, v97, v44
	v_fmac_f32_e32 v14, v97, v43
	v_fmac_f32_e32 v15, v97, v42
	v_fmac_f32_e32 v16, v97, v41
	v_fmac_f32_e32 v17, v97, v40
	v_fmac_f32_e32 v82, v97, v39
	v_fmac_f32_e32 v83, v97, v38
	v_fmac_f32_e32 v84, v97, v37
	v_fmac_f32_e32 v85, v97, v36
	v_fmac_f32_e32 v86, v97, v35
	v_fmac_f32_e32 v87, v97, v34
	v_fmac_f32_e32 v88, v97, v33
	v_fmac_f32_e32 v89, v97, v32
	v_fmac_f32_e32 v90, v97, v31
	v_fmac_f32_e32 v91, v97, v30
	v_fmac_f32_e32 v92, v97, v29
	v_fmac_f32_e32 v93, v97, v28
	v_fmac_f32_e32 v94, v97, v27
	v_fmac_f32_e32 v95, v97, v26
	v_fmac_f32_e32 v96, v97, v25
	v_fma_f32 v97, v97, v24, v55
	ds_read2st64_b32 v[102:103], v58 offset0:120 offset1:124
	s_waitcnt lgkmcnt(2)
	v_fmac_f32_e32 v8, v98, v50
	v_fmac_f32_e32 v9, v98, v49
	v_fmac_f32_e32 v10, v98, v48
	v_fmac_f32_e32 v11, v98, v47
	v_fmac_f32_e32 v12, v98, v46
	v_fmac_f32_e32 v13, v98, v45
	v_fmac_f32_e32 v14, v98, v44
	v_fmac_f32_e32 v15, v98, v43
	v_fmac_f32_e32 v16, v98, v42
	v_fmac_f32_e32 v17, v98, v41
	v_fmac_f32_e32 v82, v98, v40
	v_fmac_f32_e32 v83, v98, v39
	v_fmac_f32_e32 v84, v98, v38
	v_fmac_f32_e32 v85, v98, v37
	v_fmac_f32_e32 v86, v98, v36
	v_fmac_f32_e32 v87, v98, v35
	v_fmac_f32_e32 v88, v98, v34
	v_fmac_f32_e32 v89, v98, v33
	v_fmac_f32_e32 v90, v98, v32
	v_fmac_f32_e32 v91, v98, v31
	v_fmac_f32_e32 v92, v98, v30
	v_fmac_f32_e32 v93, v98, v29
	v_fmac_f32_e32 v94, v98, v28
	v_fmac_f32_e32 v95, v98, v27
	v_fmac_f32_e32 v96, v98, v26
	v_fmac_f32_e32 v97, v98, v25
	v_fma_f32 v98, v98, v24, v55
	v_fmac_f32_e32 v8, v99, v51
	v_fmac_f32_e32 v9, v99, v50
	v_fmac_f32_e32 v10, v99, v49
	v_fmac_f32_e32 v11, v99, v48
	v_fmac_f32_e32 v12, v99, v47
	v_fmac_f32_e32 v13, v99, v46
	v_fmac_f32_e32 v14, v99, v45
	v_fmac_f32_e32 v15, v99, v44
	v_fmac_f32_e32 v16, v99, v43
	v_fmac_f32_e32 v17, v99, v42
	v_fmac_f32_e32 v82, v99, v41
	v_fmac_f32_e32 v83, v99, v40
	v_fmac_f32_e32 v84, v99, v39
	v_fmac_f32_e32 v85, v99, v38
	v_fmac_f32_e32 v86, v99, v37
	v_fmac_f32_e32 v87, v99, v36
	v_fmac_f32_e32 v88, v99, v35
	v_fmac_f32_e32 v89, v99, v34
	v_fmac_f32_e32 v90, v99, v33
	v_fmac_f32_e32 v91, v99, v32
	v_fmac_f32_e32 v92, v99, v31
	v_fmac_f32_e32 v93, v99, v30
	v_fmac_f32_e32 v94, v99, v29
	v_fmac_f32_e32 v95, v99, v28
	v_fmac_f32_e32 v96, v99, v27
	v_fmac_f32_e32 v97, v99, v26
	v_fmac_f32_e32 v98, v99, v25
	v_fma_f32 v99, v99, v24, v55
	ds_read2st64_b32 v[104:105], v58 offset0:128 offset1:132
	s_waitcnt lgkmcnt(2)
	v_fmac_f32_e32 v8, v100, v52
	v_fmac_f32_e32 v9, v100, v51
	v_fmac_f32_e32 v10, v100, v50
	v_fmac_f32_e32 v11, v100, v49
	v_fmac_f32_e32 v12, v100, v48
	v_fmac_f32_e32 v13, v100, v47
	v_fmac_f32_e32 v14, v100, v46
	v_fmac_f32_e32 v15, v100, v45
	v_fmac_f32_e32 v16, v100, v44
	v_fmac_f32_e32 v17, v100, v43
	v_fmac_f32_e32 v82, v100, v42
	v_fmac_f32_e32 v83, v100, v41
	v_fmac_f32_e32 v84, v100, v40
	v_fmac_f32_e32 v85, v100, v39
	v_fmac_f32_e32 v86, v100, v38
	v_fmac_f32_e32 v87, v100, v37
	v_fmac_f32_e32 v88, v100, v36
	v_fmac_f32_e32 v89, v100, v35
	v_fmac_f32_e32 v90, v100, v34
	v_fmac_f32_e32 v91, v100, v33
	v_fmac_f32_e32 v92, v100, v32
	v_fmac_f32_e32 v93, v100, v31
	v_fmac_f32_e32 v94, v100, v30
	v_fmac_f32_e32 v95, v100, v29
	v_fmac_f32_e32 v96, v100, v28
	v_fmac_f32_e32 v97, v100, v27
	v_fmac_f32_e32 v98, v100, v26
	v_fmac_f32_e32 v99, v100, v25
	v_fma_f32 v100, v100, v24, v55
	v_fmac_f32_e32 v8, v101, v53
	v_fmac_f32_e32 v9, v101, v52
	v_fmac_f32_e32 v10, v101, v51
	v_fmac_f32_e32 v11, v101, v50
	v_fmac_f32_e32 v12, v101, v49
	v_fmac_f32_e32 v13, v101, v48
	v_fmac_f32_e32 v14, v101, v47
	v_fmac_f32_e32 v15, v101, v46
	v_fmac_f32_e32 v16, v101, v45
	v_fmac_f32_e32 v17, v101, v44
	v_fmac_f32_e32 v82, v101, v43
	v_fmac_f32_e32 v83, v101, v42
	v_fmac_f32_e32 v84, v101, v41
	v_fmac_f32_e32 v85, v101, v40
	v_fmac_f32_e32 v86, v101, v39
	v_fmac_f32_e32 v87, v101, v38
	v_fmac_f32_e32 v88, v101, v37
	v_fmac_f32_e32 v89, v101, v36
	v_fmac_f32_e32 v90, v101, v35
	v_fmac_f32_e32 v91, v101, v34
	v_fmac_f32_e32 v92, v101, v33
	v_fmac_f32_e32 v93, v101, v32
	v_fmac_f32_e32 v94, v101, v31
	v_fmac_f32_e32 v95, v101, v30
	v_fmac_f32_e32 v96, v101, v29
	v_fmac_f32_e32 v97, v101, v28
	v_fmac_f32_e32 v98, v101, v27
	v_fmac_f32_e32 v99, v101, v26
	v_fmac_f32_e32 v100, v101, v25
	v_fma_f32 v101, v101, v24, v55
	s_waitcnt lgkmcnt(1)
	v_fmac_f32_e32 v8, v102, v54
	v_fmac_f32_e32 v9, v102, v53
	v_fmac_f32_e32 v10, v102, v52
	v_fmac_f32_e32 v11, v102, v51
	v_fmac_f32_e32 v12, v102, v50
	v_fmac_f32_e32 v13, v102, v49
	v_fmac_f32_e32 v14, v102, v48
	v_fmac_f32_e32 v15, v102, v47
	v_fmac_f32_e32 v16, v102, v46
	v_fmac_f32_e32 v17, v102, v45
	v_fmac_f32_e32 v82, v102, v44
	v_fmac_f32_e32 v83, v102, v43
	v_fmac_f32_e32 v84, v102, v42
	v_fmac_f32_e32 v85, v102, v41
	v_fmac_f32_e32 v86, v102, v40
	v_fmac_f32_e32 v87, v102, v39
	v_fmac_f32_e32 v88, v102, v38
	v_fmac_f32_e32 v89, v102, v37
	v_fmac_f32_e32 v90, v102, v36
	v_fmac_f32_e32 v91, v102, v35
	v_fmac_f32_e32 v92, v102, v34
	v_fmac_f32_e32 v93, v102, v33
	v_fmac_f32_e32 v94, v102, v32
	v_fmac_f32_e32 v95, v102, v31
	v_fmac_f32_e32 v96, v102, v30
	v_fmac_f32_e32 v97, v102, v29
	v_fmac_f32_e32 v98, v102, v28
	v_fmac_f32_e32 v99, v102, v27
	v_fmac_f32_e32 v100, v102, v26
	v_fmac_f32_e32 v101, v102, v25
	v_fma_f32 v102, v102, v24, v55
	v_fmac_f32_e32 v9, v103, v54
	v_fmac_f32_e32 v10, v103, v53
	v_fmac_f32_e32 v11, v103, v52
	v_fmac_f32_e32 v12, v103, v51
	v_fmac_f32_e32 v13, v103, v50
	v_fmac_f32_e32 v14, v103, v49
	v_fmac_f32_e32 v15, v103, v48
	v_fmac_f32_e32 v16, v103, v47
	v_fmac_f32_e32 v17, v103, v46
	v_fmac_f32_e32 v82, v103, v45
	v_fmac_f32_e32 v83, v103, v44
	v_fmac_f32_e32 v84, v103, v43
	v_fmac_f32_e32 v85, v103, v42
	v_fmac_f32_e32 v86, v103, v41
	v_fmac_f32_e32 v87, v103, v40
	v_fmac_f32_e32 v88, v103, v39
	v_fmac_f32_e32 v89, v103, v38
	v_fmac_f32_e32 v90, v103, v37
	v_fmac_f32_e32 v91, v103, v36
	v_fmac_f32_e32 v92, v103, v35
	v_fmac_f32_e32 v93, v103, v34
	v_fmac_f32_e32 v94, v103, v33
	v_fmac_f32_e32 v95, v103, v32
	v_fmac_f32_e32 v96, v103, v31
	v_fmac_f32_e32 v97, v103, v30
	v_fmac_f32_e32 v98, v103, v29
	v_fmac_f32_e32 v99, v103, v28
	v_fmac_f32_e32 v100, v103, v27
	v_fmac_f32_e32 v101, v103, v26
	v_fmac_f32_e32 v102, v103, v25
	v_fma_f32 v103, v103, v24, v55
	s_waitcnt lgkmcnt(0)
	v_fmac_f32_e32 v11, v104, v53
	v_fmac_f32_e32 v12, v104, v52
	v_fmac_f32_e32 v13, v104, v51
	v_fmac_f32_e32 v14, v104, v50
	v_fmac_f32_e32 v15, v104, v49
	v_fmac_f32_e32 v16, v104, v48
	v_fmac_f32_e32 v17, v104, v47
	v_fmac_f32_e32 v82, v104, v46
	v_fmac_f32_e32 v83, v104, v45
	v_fmac_f32_e32 v84, v104, v44
	v_fmac_f32_e32 v85, v104, v43
	v_fmac_f32_e32 v86, v104, v42
	v_fmac_f32_e32 v87, v104, v41
	v_fmac_f32_e32 v88, v104, v40
	v_fmac_f32_e32 v89, v104, v39
	v_fmac_f32_e32 v90, v104, v38
	v_fmac_f32_e32 v91, v104, v37
	v_fmac_f32_e32 v92, v104, v36
	v_fmac_f32_e32 v93, v104, v35
	v_fmac_f32_e32 v94, v104, v34
	v_fmac_f32_e32 v95, v104, v33
	v_fmac_f32_e32 v96, v104, v32
	v_fmac_f32_e32 v97, v104, v31
	v_fmac_f32_e32 v98, v104, v30
	v_fmac_f32_e32 v99, v104, v29
	v_fmac_f32_e32 v100, v104, v28
	v_fmac_f32_e32 v101, v104, v27
	v_fmac_f32_e32 v102, v104, v26
	v_fmac_f32_e32 v103, v104, v25
	v_fmac_f32_e32 v10, v104, v54
	v_fmac_f32_e32 v11, v105, v54
	v_fmac_f32_e32 v12, v105, v53
	v_fmac_f32_e32 v13, v105, v52
	v_fmac_f32_e32 v14, v105, v51
	v_fmac_f32_e32 v15, v105, v50
	v_fmac_f32_e32 v16, v105, v49
	v_fmac_f32_e32 v17, v105, v48
	v_fmac_f32_e32 v82, v105, v47
	v_fmac_f32_e32 v83, v105, v46
	v_fmac_f32_e32 v84, v105, v45
	v_fmac_f32_e32 v85, v105, v44
	v_fmac_f32_e32 v86, v105, v43
	v_fmac_f32_e32 v87, v105, v42
	v_fmac_f32_e32 v88, v105, v41
	v_fmac_f32_e32 v89, v105, v40
	v_fmac_f32_e32 v90, v105, v39
	v_fmac_f32_e32 v91, v105, v38
	v_fmac_f32_e32 v92, v105, v37
	v_fmac_f32_e32 v93, v105, v36
	v_fmac_f32_e32 v94, v105, v35
	v_fmac_f32_e32 v95, v105, v34
	v_fmac_f32_e32 v96, v105, v33
	v_fmac_f32_e32 v97, v105, v32
	v_fmac_f32_e32 v98, v105, v31
	v_fmac_f32_e32 v99, v105, v30
	v_fmac_f32_e32 v100, v105, v29
	v_fmac_f32_e32 v101, v105, v28
	v_fmac_f32_e32 v102, v105, v27
	v_fmac_f32_e32 v103, v105, v26
	ds_read2st64_b32 v[104:105], v58 offset0:136 offset1:140
	s_mov_b32 s4, 0
	s_waitcnt lgkmcnt(0)
	v_fmac_f32_e32 v13, v104, v53
	v_fmac_f32_e32 v14, v104, v52
	v_fmac_f32_e32 v15, v104, v51
	v_fmac_f32_e32 v16, v104, v50
	v_fmac_f32_e32 v17, v104, v49
	v_fmac_f32_e32 v82, v104, v48
	v_fmac_f32_e32 v83, v104, v47
	v_fmac_f32_e32 v84, v104, v46
	v_fmac_f32_e32 v85, v104, v45
	v_fmac_f32_e32 v86, v104, v44
	v_fmac_f32_e32 v87, v104, v43
	v_fmac_f32_e32 v88, v104, v42
	v_fmac_f32_e32 v89, v104, v41
	v_fmac_f32_e32 v90, v104, v40
	v_fmac_f32_e32 v91, v104, v39
	v_fmac_f32_e32 v92, v104, v38
	v_fmac_f32_e32 v93, v104, v37
	v_fmac_f32_e32 v94, v104, v36
	v_fmac_f32_e32 v95, v104, v35
	v_fmac_f32_e32 v96, v104, v34
	v_fmac_f32_e32 v97, v104, v33
	v_fmac_f32_e32 v98, v104, v32
	v_fmac_f32_e32 v99, v104, v31
	v_fmac_f32_e32 v100, v104, v30
	v_fmac_f32_e32 v101, v104, v29
	v_fmac_f32_e32 v102, v104, v28
	v_fmac_f32_e32 v103, v104, v27
	v_fmac_f32_e32 v12, v104, v54
	v_fmac_f32_e32 v13, v105, v54
	v_fmac_f32_e32 v14, v105, v53
	v_fmac_f32_e32 v15, v105, v52
	v_fmac_f32_e32 v16, v105, v51
	v_fmac_f32_e32 v17, v105, v50
	v_fmac_f32_e32 v82, v105, v49
	v_fmac_f32_e32 v83, v105, v48
	v_fmac_f32_e32 v84, v105, v47
	v_fmac_f32_e32 v85, v105, v46
	v_fmac_f32_e32 v86, v105, v45
	v_fmac_f32_e32 v87, v105, v44
	v_fmac_f32_e32 v88, v105, v43
	v_fmac_f32_e32 v89, v105, v42
	v_fmac_f32_e32 v90, v105, v41
	v_fmac_f32_e32 v91, v105, v40
	v_fmac_f32_e32 v92, v105, v39
	v_fmac_f32_e32 v93, v105, v38
	v_fmac_f32_e32 v94, v105, v37
	v_fmac_f32_e32 v95, v105, v36
	v_fmac_f32_e32 v96, v105, v35
	v_fmac_f32_e32 v97, v105, v34
	v_fmac_f32_e32 v98, v105, v33
	v_fmac_f32_e32 v99, v105, v32
	v_fmac_f32_e32 v100, v105, v31
	v_fmac_f32_e32 v101, v105, v30
	v_fmac_f32_e32 v102, v105, v29
	v_fmac_f32_e32 v103, v105, v28
	ds_read2st64_b32 v[104:105], v58 offset0:144 offset1:148
	s_waitcnt lgkmcnt(0)
	v_fmac_f32_e32 v15, v104, v53
	v_fmac_f32_e32 v16, v104, v52
	v_fmac_f32_e32 v17, v104, v51
	v_fmac_f32_e32 v82, v104, v50
	v_fmac_f32_e32 v83, v104, v49
	v_fmac_f32_e32 v84, v104, v48
	v_fmac_f32_e32 v85, v104, v47
	v_fmac_f32_e32 v86, v104, v46
	v_fmac_f32_e32 v87, v104, v45
	v_fmac_f32_e32 v88, v104, v44
	v_fmac_f32_e32 v89, v104, v43
	v_fmac_f32_e32 v90, v104, v42
	v_fmac_f32_e32 v91, v104, v41
	v_fmac_f32_e32 v92, v104, v40
	v_fmac_f32_e32 v93, v104, v39
	v_fmac_f32_e32 v94, v104, v38
	v_fmac_f32_e32 v95, v104, v37
	v_fmac_f32_e32 v96, v104, v36
	v_fmac_f32_e32 v97, v104, v35
	v_fmac_f32_e32 v98, v104, v34
	v_fmac_f32_e32 v99, v104, v33
	v_fmac_f32_e32 v100, v104, v32
	v_fmac_f32_e32 v101, v104, v31
	v_fmac_f32_e32 v102, v104, v30
	v_fmac_f32_e32 v103, v104, v29
	v_fmac_f32_e32 v14, v104, v54
	v_fmac_f32_e32 v15, v105, v54
	v_fmac_f32_e32 v16, v105, v53
	v_fmac_f32_e32 v17, v105, v52
	v_fmac_f32_e32 v82, v105, v51
	v_fmac_f32_e32 v83, v105, v50
	v_fmac_f32_e32 v84, v105, v49
	v_fmac_f32_e32 v85, v105, v48
	v_fmac_f32_e32 v86, v105, v47
	v_fmac_f32_e32 v87, v105, v46
	v_fmac_f32_e32 v88, v105, v45
	v_fmac_f32_e32 v89, v105, v44
	v_fmac_f32_e32 v90, v105, v43
	v_fmac_f32_e32 v91, v105, v42
	v_fmac_f32_e32 v92, v105, v41
	v_fmac_f32_e32 v93, v105, v40
	v_fmac_f32_e32 v94, v105, v39
	v_fmac_f32_e32 v95, v105, v38
	v_fmac_f32_e32 v96, v105, v37
	v_fmac_f32_e32 v97, v105, v36
	v_fmac_f32_e32 v98, v105, v35
	v_fmac_f32_e32 v99, v105, v34
	v_fmac_f32_e32 v100, v105, v33
	v_fmac_f32_e32 v101, v105, v32
	v_fmac_f32_e32 v102, v105, v31
	v_fmac_f32_e32 v103, v105, v30
	ds_read2st64_b32 v[104:105], v58 offset0:152 offset1:156
	s_waitcnt lgkmcnt(0)
	v_fmac_f32_e32 v17, v104, v53
	v_fmac_f32_e32 v82, v104, v52
	v_fmac_f32_e32 v83, v104, v51
	v_fmac_f32_e32 v84, v104, v50
	v_fmac_f32_e32 v85, v104, v49
	v_fmac_f32_e32 v86, v104, v48
	v_fmac_f32_e32 v87, v104, v47
	v_fmac_f32_e32 v88, v104, v46
	v_fmac_f32_e32 v89, v104, v45
	v_fmac_f32_e32 v90, v104, v44
	v_fmac_f32_e32 v91, v104, v43
	v_fmac_f32_e32 v92, v104, v42
	v_fmac_f32_e32 v93, v104, v41
	v_fmac_f32_e32 v94, v104, v40
	v_fmac_f32_e32 v95, v104, v39
	v_fmac_f32_e32 v96, v104, v38
	v_fmac_f32_e32 v97, v104, v37
	v_fmac_f32_e32 v98, v104, v36
	v_fmac_f32_e32 v99, v104, v35
	v_fmac_f32_e32 v100, v104, v34
	v_fmac_f32_e32 v101, v104, v33
	v_fmac_f32_e32 v102, v104, v32
	v_fmac_f32_e32 v103, v104, v31
	v_fmac_f32_e32 v16, v104, v54
	v_fmac_f32_e32 v17, v105, v54
	v_fmac_f32_e32 v82, v105, v53
	v_fmac_f32_e32 v83, v105, v52
	v_fmac_f32_e32 v84, v105, v51
	v_fmac_f32_e32 v85, v105, v50
	v_fmac_f32_e32 v86, v105, v49
	v_fmac_f32_e32 v87, v105, v48
	v_fmac_f32_e32 v88, v105, v47
	v_fmac_f32_e32 v89, v105, v46
	v_fmac_f32_e32 v90, v105, v45
	v_fmac_f32_e32 v91, v105, v44
	v_fmac_f32_e32 v92, v105, v43
	v_fmac_f32_e32 v93, v105, v42
	v_fmac_f32_e32 v94, v105, v41
	v_fmac_f32_e32 v95, v105, v40
	v_fmac_f32_e32 v96, v105, v39
	v_fmac_f32_e32 v97, v105, v38
	v_fmac_f32_e32 v98, v105, v37
	v_fmac_f32_e32 v99, v105, v36
	v_fmac_f32_e32 v100, v105, v35
	v_fmac_f32_e32 v101, v105, v34
	v_fmac_f32_e32 v102, v105, v33
	v_fmac_f32_e32 v103, v105, v32
	ds_read2st64_b32 v[104:105], v58 offset0:160 offset1:164
	s_waitcnt lgkmcnt(0)
	v_fmac_f32_e32 v83, v104, v53
	v_fmac_f32_e32 v84, v104, v52
	v_fmac_f32_e32 v85, v104, v51
	v_fmac_f32_e32 v86, v104, v50
	v_fmac_f32_e32 v87, v104, v49
	v_fmac_f32_e32 v88, v104, v48
	v_fmac_f32_e32 v89, v104, v47
	v_fmac_f32_e32 v90, v104, v46
	v_fmac_f32_e32 v91, v104, v45
	v_fmac_f32_e32 v92, v104, v44
	v_fmac_f32_e32 v93, v104, v43
	v_fmac_f32_e32 v94, v104, v42
	v_fmac_f32_e32 v95, v104, v41
	v_fmac_f32_e32 v96, v104, v40
	v_fmac_f32_e32 v97, v104, v39
	v_fmac_f32_e32 v98, v104, v38
	v_fmac_f32_e32 v99, v104, v37
	v_fmac_f32_e32 v100, v104, v36
	v_fmac_f32_e32 v101, v104, v35
	v_fmac_f32_e32 v102, v104, v34
	v_fmac_f32_e32 v103, v104, v33
	v_fmac_f32_e32 v82, v104, v54
	v_fmac_f32_e32 v83, v105, v54
	v_fmac_f32_e32 v84, v105, v53
	v_fmac_f32_e32 v85, v105, v52
	v_fmac_f32_e32 v86, v105, v51
	v_fmac_f32_e32 v87, v105, v50
	v_fmac_f32_e32 v88, v105, v49
	v_fmac_f32_e32 v89, v105, v48
	v_fmac_f32_e32 v90, v105, v47
	v_fmac_f32_e32 v91, v105, v46
	v_fmac_f32_e32 v92, v105, v45
	v_fmac_f32_e32 v93, v105, v44
	v_fmac_f32_e32 v94, v105, v43
	v_fmac_f32_e32 v95, v105, v42
	v_fmac_f32_e32 v96, v105, v41
	v_fmac_f32_e32 v97, v105, v40
	v_fmac_f32_e32 v98, v105, v39
	v_fmac_f32_e32 v99, v105, v38
	v_fmac_f32_e32 v100, v105, v37
	v_fmac_f32_e32 v101, v105, v36
	v_fmac_f32_e32 v102, v105, v35
	v_fmac_f32_e32 v103, v105, v34
	ds_read2st64_b32 v[104:105], v58 offset0:168 offset1:172
	s_waitcnt lgkmcnt(0)
	v_fmac_f32_e32 v85, v104, v53
	v_fmac_f32_e32 v86, v104, v52
	v_fmac_f32_e32 v87, v104, v51
	v_fmac_f32_e32 v88, v104, v50
	v_fmac_f32_e32 v89, v104, v49
	v_fmac_f32_e32 v90, v104, v48
	v_fmac_f32_e32 v91, v104, v47
	v_fmac_f32_e32 v92, v104, v46
	v_fmac_f32_e32 v93, v104, v45
	v_fmac_f32_e32 v94, v104, v44
	v_fmac_f32_e32 v95, v104, v43
	v_fmac_f32_e32 v96, v104, v42
	v_fmac_f32_e32 v97, v104, v41
	v_fmac_f32_e32 v98, v104, v40
	v_fmac_f32_e32 v99, v104, v39
	v_fmac_f32_e32 v100, v104, v38
	v_fmac_f32_e32 v101, v104, v37
	v_fmac_f32_e32 v102, v104, v36
	v_fmac_f32_e32 v103, v104, v35
	v_fmac_f32_e32 v84, v104, v54
	v_fmac_f32_e32 v85, v105, v54
	v_fmac_f32_e32 v86, v105, v53
	v_fmac_f32_e32 v87, v105, v52
	v_fmac_f32_e32 v88, v105, v51
	v_fmac_f32_e32 v89, v105, v50
	v_fmac_f32_e32 v90, v105, v49
	v_fmac_f32_e32 v91, v105, v48
	v_fmac_f32_e32 v92, v105, v47
	v_fmac_f32_e32 v93, v105, v46
	v_fmac_f32_e32 v94, v105, v45
	v_fmac_f32_e32 v95, v105, v44
	v_fmac_f32_e32 v96, v105, v43
	v_fmac_f32_e32 v97, v105, v42
	v_fmac_f32_e32 v98, v105, v41
	v_fmac_f32_e32 v99, v105, v40
	v_fmac_f32_e32 v100, v105, v39
	v_fmac_f32_e32 v101, v105, v38
	v_fmac_f32_e32 v102, v105, v37
	v_fmac_f32_e32 v103, v105, v36
	ds_read2st64_b32 v[104:105], v58 offset0:176 offset1:180
	s_waitcnt lgkmcnt(0)
	v_fmac_f32_e32 v87, v104, v53
	v_fmac_f32_e32 v88, v104, v52
	v_fmac_f32_e32 v89, v104, v51
	v_fmac_f32_e32 v90, v104, v50
	v_fmac_f32_e32 v91, v104, v49
	v_fmac_f32_e32 v92, v104, v48
	v_fmac_f32_e32 v93, v104, v47
	v_fmac_f32_e32 v94, v104, v46
	v_fmac_f32_e32 v95, v104, v45
	v_fmac_f32_e32 v96, v104, v44
	v_fmac_f32_e32 v97, v104, v43
	v_fmac_f32_e32 v98, v104, v42
	v_fmac_f32_e32 v99, v104, v41
	v_fmac_f32_e32 v100, v104, v40
	v_fmac_f32_e32 v101, v104, v39
	v_fmac_f32_e32 v102, v104, v38
	v_fmac_f32_e32 v103, v104, v37
	v_fmac_f32_e32 v86, v104, v54
	v_fmac_f32_e32 v87, v105, v54
	v_fmac_f32_e32 v88, v105, v53
	v_fmac_f32_e32 v89, v105, v52
	v_fmac_f32_e32 v90, v105, v51
	v_fmac_f32_e32 v91, v105, v50
	v_fmac_f32_e32 v92, v105, v49
	v_fmac_f32_e32 v93, v105, v48
	v_fmac_f32_e32 v94, v105, v47
	v_fmac_f32_e32 v95, v105, v46
	v_fmac_f32_e32 v96, v105, v45
	v_fmac_f32_e32 v97, v105, v44
	v_fmac_f32_e32 v98, v105, v43
	v_fmac_f32_e32 v99, v105, v42
	v_fmac_f32_e32 v100, v105, v41
	v_fmac_f32_e32 v101, v105, v40
	v_fmac_f32_e32 v102, v105, v39
	v_fmac_f32_e32 v103, v105, v38
	ds_read2st64_b32 v[104:105], v58 offset0:184 offset1:188
	s_waitcnt lgkmcnt(0)
	v_fmac_f32_e32 v89, v104, v53
	v_fmac_f32_e32 v90, v104, v52
	v_fmac_f32_e32 v91, v104, v51
	v_fmac_f32_e32 v92, v104, v50
	v_fmac_f32_e32 v93, v104, v49
	v_fmac_f32_e32 v94, v104, v48
	v_fmac_f32_e32 v95, v104, v47
	v_fmac_f32_e32 v96, v104, v46
	v_fmac_f32_e32 v97, v104, v45
	v_fmac_f32_e32 v98, v104, v44
	v_fmac_f32_e32 v99, v104, v43
	v_fmac_f32_e32 v100, v104, v42
	v_fmac_f32_e32 v101, v104, v41
	v_fmac_f32_e32 v102, v104, v40
	v_fmac_f32_e32 v103, v104, v39
	v_fmac_f32_e32 v88, v104, v54
	v_fmac_f32_e32 v89, v105, v54
	v_fmac_f32_e32 v90, v105, v53
	v_fmac_f32_e32 v91, v105, v52
	v_fmac_f32_e32 v92, v105, v51
	v_fmac_f32_e32 v93, v105, v50
	v_fmac_f32_e32 v94, v105, v49
	v_fmac_f32_e32 v95, v105, v48
	v_fmac_f32_e32 v96, v105, v47
	v_fmac_f32_e32 v97, v105, v46
	v_fmac_f32_e32 v98, v105, v45
	v_fmac_f32_e32 v99, v105, v44
	v_fmac_f32_e32 v100, v105, v43
	v_fmac_f32_e32 v101, v105, v42
	v_fmac_f32_e32 v102, v105, v41
	v_fmac_f32_e32 v103, v105, v40
	ds_read2st64_b32 v[104:105], v58 offset0:192 offset1:196
	s_waitcnt lgkmcnt(0)
	v_fmac_f32_e32 v91, v104, v53
	v_fmac_f32_e32 v92, v104, v52
	v_fmac_f32_e32 v93, v104, v51
	v_fmac_f32_e32 v94, v104, v50
	v_fmac_f32_e32 v95, v104, v49
	v_fmac_f32_e32 v96, v104, v48
	v_fmac_f32_e32 v97, v104, v47
	v_fmac_f32_e32 v98, v104, v46
	v_fmac_f32_e32 v99, v104, v45
	v_fmac_f32_e32 v100, v104, v44
	v_fmac_f32_e32 v101, v104, v43
	v_fmac_f32_e32 v102, v104, v42
	v_fmac_f32_e32 v103, v104, v41
	v_fmac_f32_e32 v90, v104, v54
	v_fmac_f32_e32 v91, v105, v54
	v_fmac_f32_e32 v92, v105, v53
	v_fmac_f32_e32 v93, v105, v52
	v_fmac_f32_e32 v94, v105, v51
	v_fmac_f32_e32 v95, v105, v50
	v_fmac_f32_e32 v96, v105, v49
	v_fmac_f32_e32 v97, v105, v48
	v_fmac_f32_e32 v98, v105, v47
	v_fmac_f32_e32 v99, v105, v46
	v_fmac_f32_e32 v100, v105, v45
	v_fmac_f32_e32 v101, v105, v44
	v_fmac_f32_e32 v102, v105, v43
	v_fmac_f32_e32 v103, v105, v42
	ds_read2st64_b32 v[104:105], v58 offset0:200 offset1:204
	s_waitcnt lgkmcnt(0)
	v_fmac_f32_e32 v93, v104, v53
	v_fmac_f32_e32 v94, v104, v52
	v_fmac_f32_e32 v95, v104, v51
	v_fmac_f32_e32 v96, v104, v50
	v_fmac_f32_e32 v97, v104, v49
	v_fmac_f32_e32 v98, v104, v48
	v_fmac_f32_e32 v99, v104, v47
	v_fmac_f32_e32 v100, v104, v46
	v_fmac_f32_e32 v101, v104, v45
	v_fmac_f32_e32 v102, v104, v44
	v_fmac_f32_e32 v103, v104, v43
	v_fmac_f32_e32 v92, v104, v54
	v_fmac_f32_e32 v93, v105, v54
	v_fmac_f32_e32 v94, v105, v53
	v_fmac_f32_e32 v95, v105, v52
	v_fmac_f32_e32 v96, v105, v51
	v_fmac_f32_e32 v97, v105, v50
	v_fmac_f32_e32 v98, v105, v49
	v_fmac_f32_e32 v99, v105, v48
	v_fmac_f32_e32 v100, v105, v47
	v_fmac_f32_e32 v101, v105, v46
	v_fmac_f32_e32 v102, v105, v45
	v_fmac_f32_e32 v103, v105, v44
	ds_read2st64_b32 v[104:105], v58 offset0:208 offset1:212
	s_waitcnt lgkmcnt(0)
	v_fmac_f32_e32 v95, v104, v53
	v_fmac_f32_e32 v96, v104, v52
	v_fmac_f32_e32 v97, v104, v51
	v_fmac_f32_e32 v98, v104, v50
	v_fmac_f32_e32 v99, v104, v49
	v_fmac_f32_e32 v100, v104, v48
	v_fmac_f32_e32 v101, v104, v47
	v_fmac_f32_e32 v102, v104, v46
	v_fmac_f32_e32 v103, v104, v45
	v_fmac_f32_e32 v94, v104, v54
	v_fmac_f32_e32 v95, v105, v54
	v_fmac_f32_e32 v96, v105, v53
	v_fmac_f32_e32 v97, v105, v52
	v_fmac_f32_e32 v98, v105, v51
	v_fmac_f32_e32 v99, v105, v50
	v_fmac_f32_e32 v100, v105, v49
	v_fmac_f32_e32 v101, v105, v48
	v_fmac_f32_e32 v102, v105, v47
	v_fmac_f32_e32 v103, v105, v46
	ds_read2st64_b32 v[104:105], v58 offset0:216 offset1:220
	s_waitcnt lgkmcnt(0)
	v_fmac_f32_e32 v97, v104, v53
	v_fmac_f32_e32 v98, v104, v52
	v_fmac_f32_e32 v99, v104, v51
	v_fmac_f32_e32 v100, v104, v50
	v_fmac_f32_e32 v101, v104, v49
	v_fmac_f32_e32 v102, v104, v48
	v_fmac_f32_e32 v103, v104, v47
	v_fmac_f32_e32 v96, v104, v54
	v_fmac_f32_e32 v97, v105, v54
	v_fmac_f32_e32 v98, v105, v53
	v_fmac_f32_e32 v99, v105, v52
	v_fmac_f32_e32 v100, v105, v51
	v_fmac_f32_e32 v101, v105, v50
	v_fmac_f32_e32 v102, v105, v49
	v_fmac_f32_e32 v103, v105, v48
	ds_read2st64_b32 v[104:105], v58 offset0:224 offset1:228
	s_waitcnt lgkmcnt(0)
	v_fmac_f32_e32 v99, v104, v53
	v_fmac_f32_e32 v100, v104, v52
	v_fmac_f32_e32 v101, v104, v51
	v_fmac_f32_e32 v102, v104, v50
	v_fmac_f32_e32 v103, v104, v49
	v_fmac_f32_e32 v98, v104, v54
	v_fmac_f32_e32 v99, v105, v54
	v_fmac_f32_e32 v100, v105, v53
	v_fmac_f32_e32 v101, v105, v52
	v_fmac_f32_e32 v102, v105, v51
	v_fmac_f32_e32 v103, v105, v50
	ds_read2st64_b32 v[104:105], v58 offset0:232 offset1:236
	s_waitcnt lgkmcnt(0)
	v_fmac_f32_e32 v101, v104, v53
	v_fmac_f32_e32 v102, v104, v52
	v_fmac_f32_e32 v103, v104, v51
	v_fmac_f32_e32 v100, v104, v54
	v_fmac_f32_e32 v101, v105, v54
	v_fmac_f32_e32 v102, v105, v53
	v_fmac_f32_e32 v103, v105, v52
	ds_read2st64_b32 v[104:105], v58 offset0:240 offset1:244
	s_waitcnt lgkmcnt(0)
	s_barrier
	v_fmac_f32_e32 v103, v104, v53
	v_fmac_f32_e32 v102, v104, v54
	v_fmac_f32_e32 v103, v105, v54
	ds_write2st64_b32 v58, v8, v9 offset1:4
	ds_write2st64_b32 v58, v10, v11 offset0:8 offset1:12
	ds_write2st64_b32 v58, v12, v13 offset0:16 offset1:20
	ds_write2st64_b32 v58, v14, v15 offset0:24 offset1:28
	ds_write2st64_b32 v58, v16, v17 offset0:32 offset1:36
	ds_write2st64_b32 v58, v82, v83 offset0:40 offset1:44
	ds_write2st64_b32 v58, v84, v85 offset0:48 offset1:52
	ds_write2st64_b32 v58, v86, v87 offset0:56 offset1:60
	ds_write2st64_b32 v58, v88, v89 offset0:64 offset1:68
	ds_write2st64_b32 v58, v90, v91 offset0:72 offset1:76
	ds_write2st64_b32 v58, v92, v93 offset0:80 offset1:84
	ds_write2st64_b32 v58, v94, v95 offset0:88 offset1:92
	ds_write2st64_b32 v58, v96, v97 offset0:96 offset1:100
	ds_write2st64_b32 v58, v98, v99 offset0:104 offset1:108
	ds_write2st64_b32 v58, v100, v101 offset0:112 offset1:116
	ds_write2st64_b32 v58, v102, v103 offset0:120 offset1:124
	v_add_u32_e32 v8, s99, v72
	s_waitcnt lgkmcnt(0)
	s_barrier
	s_waitcnt vmcnt(0)

.LBB0_504:
	s_and_b32 s98, s29, 0xffffff03
	s_lshr_b32 s99, s29, 1
	s_and_b32 s99, s99, 0x7c
	s_or_b32 s98, s98, s99
	s_and_b32 s99, s29, 4
	s_lshl_b32 s99, s99, 5
	s_or_b32 s98, s98, s99
	s_ashr_i32 s0, s98, 4
	s_cmpk_gt_i32 s0, 0x7f
	s_mov_b64 s[8:9], -1
	s_cbranch_scc0 .LBB0_506
	s_lshl_b32 s6, s0, 9
	s_add_i32 s6, s6, 0x7fff0000
	s_and_b32 s6, s6, 0x7fffe000
	s_add_i32 s6, s6, 0x10000
	s_mov_b64 s[8:9], 0
.LBB0_506:
	s_andn2_b64 vcc, exec, s[8:9]
	s_cbranch_vccnz .LBB0_508
	s_lshl_b32 s6, s98, 5
	s_and_b32 s6, s6, 0xfffff000
	s_mov_b32 s18, 56
	s_mov_b32 s7, 7
	s_bfe_u32 s19, s98, 0x20002
	s_cmp_lt_i32 s19, 1
	s_mov_b32 s8, s19
	s_cbranch_scc0 .LBB0_509
	s_branch .LBB0_513
.LBB0_508:
	s_movk_i32 s18, 0x78
	s_mov_b32 s7, 15
	s_bfe_u32 s19, s98, 0x20002
	s_cmp_lt_i32 s19, 1
	s_mov_b32 s8, s19
	s_cbranch_scc1 .LBB0_513

.LBB0_513:
	s_and_b32 s9, s98, 3
	s_and_b32 s0, s7, s0
	s_lshl_b32 s17, s0, 3
	s_add_i32 s7, s17, -4
	s_min_i32 s7, s7, s18
	s_cmp_lg_u32 s0, 0
	s_cselect_b32 s16, s7, 0
	s_or_b32 s0, s17, 3
	s_min_u32 s0, s0, s18
	s_sub_i32 s7, s0, s16
	s_add_i32 s7, s7, 8
	s_movk_i32 s79, 0x88
	v_readfirstlane_b32 s10, v195
	v_and_b32_e32 v0, 7, v195
	v_bfe_u32 v1, v195, 3, 5
	v_lshlrev_b32_e32 v2, 4, v0
	v_lshl_add_u32 v146, v1, 9, v2
	v_mad_u32_u24 v147, v1, s79, v2
	v_and_b32_e32 v3, 63, v195
	v_and_b32_e32 v4, 3, v3
	v_lshlrev_b32_e32 v4, 4, v4
	v_bfe_u32 v5, v3, 2, 2
	v_lshrrev_b32_e32 v6, 4, v3
	v_mul_u32_u24_e32 v206, 0x28000, v6
	v_lshl_add_u32 v206, v5, 7, v206
	v_add_u32_e32 v206, v206, v4
	v_mul_u32_u24_e32 v207, 0x3d0, v6
	v_lshl_add_u32 v207, v5, 6, v207
	v_add_u32_e32 v207, v207, v4
	v_lshlrev_b32_e32 v7, 2, v195
	v_add_u32_e32 v8, 0x1f300, v7
	s_lshr_b32 s11, s10, 8
	s_lshr_b32 s10, s10, 6
	s_mul_i32 s14, s11, 0x1100
	v_add_u32_e32 v147, s14, v147
	s_and_b32 s14, s10, 1
	s_lshl_b32 s14, s14, 4
	s_lshr_b32 s15, s10, 1
	s_lshl_b32 s15, s15, 2
	s_add_i32 s14, s14, s15
	s_mulk_i32 s14, 0x3d0
	s_add_i32 s14, s14, 0xff00
	v_add_u32_e32 v207, s14, v207
	s_or_b32 s14, s9, s25
	s_mulk_i32 s14, 0x744
	s_add_u32 s30, s60, s14
	s_addc_u32 s31, s61, 0
	s_and_saveexec_b64 s[34:35], s[2:3]
	global_load_dword v9, v7, s[30:31]
	s_mov_b64 exec, s[34:35]
	v_readlane_b32 s12, v254, 2
	v_readlane_b32 s13, v254, 3
	s_add_i32 s14, s16, s11
	s_lshl_b32 s14, s14, 6
	s_add_i32 s14, s14, s6
	s_add_i32 s14, s14, s8
	s_lshl_b32 s14, s14, 9
	s_lshl_b32 s15, s9, 7
	s_add_u32 s14, s14, s15
	s_add_u32 s12, s12, s14
	s_addc_u32 s13, s13, 0
	s_sub_i32 s0, s7, s11
	global_load_dwordx4 v[148:151], v146, s[12:13]
	s_add_u32 s12, s12, 0x10000
	s_addc_u32 s13, s13, 0
	global_load_dwordx4 v[152:155], v146, s[12:13]
	s_add_u32 s12, s12, 0x10000
	s_addc_u32 s13, s13, 0
	global_load_dwordx4 v[156:159], v146, s[12:13]
	s_add_u32 s12, s12, 0x10000
	s_addc_u32 s13, s13, 0
	global_load_dwordx4 v[160:163], v146, s[12:13]
	s_cmp_gt_i32 s0, 8
	s_cbranch_scc0 .Lna_kld_done
	s_add_u32 s12, s12, 0x10000
	s_addc_u32 s13, s13, 0
	global_load_dwordx4 v[164:167], v146, s[12:13]
	s_cmp_gt_i32 s0, 10
	s_cbranch_scc0 .Lna_kld_done
	s_add_u32 s12, s12, 0x10000
	s_addc_u32 s13, s13, 0
	global_load_dwordx4 v[168:171], v146, s[12:13]
	s_cmp_gt_i32 s0, 12
	s_cbranch_scc0 .Lna_kld_done
	s_add_u32 s12, s12, 0x10000
	s_addc_u32 s13, s13, 0
	global_load_dwordx4 v[172:175], v146, s[12:13]
	s_cmp_gt_i32 s0, 14
	s_cbranch_scc0 .Lna_kld_done
	s_add_u32 s12, s12, 0x10000
	s_addc_u32 s13, s13, 0
	global_load_dwordx4 v[176:179], v146, s[12:13]

.LBB0_680:
	s_and_b32 s100, s22, 0xffffff01
	s_lshr_b32 s101, s22, 2
	s_and_b32 s101, s101, 0x3e
	s_or_b32 s100, s100, s101
	s_and_b32 s101, s22, 6
	s_lshl_b32 s101, s101, 5
	s_or_b32 s100, s100, s101
	s_and_b32 s4, s100, 1
	s_lshl_b32 s5, s100, 6
	s_and_b32 s6, s5, 0xffffff80
	s_cmp_lt_i32 s6, 0x10000
	s_movk_i32 s7, 0xf80
	s_cselect_b32 s7, s7, 0x1f80
	s_movk_i32 s8, 0x2000
	s_cselect_b32 s8, 0x1000, s8
	s_and_b32 s7, s7, s5
	v_lshrrev_b32_e32 v0, 3, v195
	v_bfe_u32 v1, v195, 2, 1
	v_and_b32_e32 v2, 3, v195
	v_lshlrev_b32_e32 v3, 6, v1
	v_lshl_or_b32 v3, v2, 4, v3
	v_mul_u32_u24_e32 v4, 0x28000, v0
	v_add_u32_e32 v146, v4, v3
	v_lshrrev_b32_e32 v4, 1, v3
	v_mul_u32_u24_e32 v4, 0x88, v4
	v_lshl_add_u32 v147, v0, 1, v4
	v_and_b32_e32 v4, 35, v0
	v_bfe_u32 v5, v0, 2, 1
	v_lshl_or_b32 v4, v5, 4, v4
	v_bfe_u32 v5, v0, 3, 2
	v_lshl_or_b32 v4, v5, 2, v4
	v_mul_u32_u24_e32 v4, 0x310, v4
	v_add_u32_e32 v206, v4, v3
	s_lshl_b32 s9, s6, 1
	s_mul_i32 s10, s4, 0xa00000
	s_add_u32 s9, s9, s10
	v_readlane_b32 s10, v254, 9
	v_readlane_b32 s11, v254, 10
	s_add_u32 s10, s10, s9
	s_addc_u32 s11, s11, 0
	v_readlane_b32 s12, v254, 11
	v_readlane_b32 s13, v254, 12
	s_add_u32 s12, s12, s9
	s_addc_u32 s13, s13, 0
	s_nop 1
	global_load_dwordx4 v[156:159], v146, s[10:11]
	global_load_dwordx4 v[160:163], v146, s[10:11] offset:128
	global_load_dwordx4 v[180:183], v146, s[12:13]
	global_load_dwordx4 v[184:187], v146, s[12:13] offset:128
	s_cmp_lg_u32 s7, 0
	s_cbranch_scc0 .Lswa_lo_zero
	global_load_dwordx4 v[148:151], v146, s[10:11] offset:-256
	global_load_dwordx4 v[152:155], v146, s[10:11] offset:-128
	global_load_dwordx4 v[172:175], v146, s[12:13] offset:-256
	global_load_dwordx4 v[176:179], v146, s[12:13] offset:-128
	s_branch .Lswa_lo_done

.Lswa_hi_done:
	s_and_b32 s0, s100, 1
	s_mov_b64 s[2:3], exec
	v_readlane_b32 s4, v254, 49
	v_readlane_b32 s5, v254, 50
	s_and_b64 s[4:5], s[2:3], s[4:5]
	s_movk_i32 s17, 0xffe0
	s_mov_b32 s20, 0x2aaaaaab
	s_movk_i32 s21, 0xfe80
	s_mov_b64 exec, s[4:5]
	s_cbranch_execz .LBB0_690
	s_lshl_b32 s8, s0, 1
	s_mov_b64 s[6:7], -1
	v_mov_b32_e32 v0, v12
	s_mov_b64 s[4:5], exec
	v_readlane_b32 s10, v255, 11
	v_readlane_b32 s11, v255, 12
	s_and_b64 s[10:11], s[4:5], s[10:11]
	s_mov_b64 exec, s[10:11]
	s_cbranch_execz .LBB0_685
	s_mov_b32 s9, s8
	s_mov_b64 s[6:7], 0
	v_mov_b32_e32 v2, v90
	v_mov_b32_e32 v3, v92
	v_mov_b64_e32 v[0:1], v[12:13]
	s_movk_i32 s10, 0x80
	s_mov_b32 s11, 0x7f807f81
	s_movk_i32 s12, 0x5a

.LBB0_690:
	s_or_b64 exec, exec, s[2:3]
	s_lshl_b32 s2, s100, 6
	s_and_b32 s15, s2, 0xffffff80
	s_cmp_lt_i32 s15, 0x10000
	s_movk_i32 s3, 0xf80
	s_cselect_b32 s3, s3, 0x1f80
	s_movk_i32 s4, 0x2000
	s_cselect_b32 s12, 0x1000, s4
	s_and_b32 s13, s3, s2
	s_add_i32 s14, s13, 0xffffff80
	s_mov_b64 s[2:3], exec
	s_waitcnt vmcnt(0)
	ds_write_b16 v147, v148 offset:0
	ds_write_b16_d16_hi v147, v148 offset:136
	ds_write_b16 v147, v149 offset:272
	ds_write_b16_d16_hi v147, v149 offset:408
	ds_write_b16 v147, v150 offset:544
	ds_write_b16_d16_hi v147, v150 offset:680
	ds_write_b16 v147, v151 offset:816
	ds_write_b16_d16_hi v147, v151 offset:952
	ds_write_b16 v147, v152 offset:8704
	ds_write_b16_d16_hi v147, v152 offset:8840
	ds_write_b16 v147, v153 offset:8976
	ds_write_b16_d16_hi v147, v153 offset:9112
	ds_write_b16 v147, v154 offset:9248
	ds_write_b16_d16_hi v147, v154 offset:9384
	ds_write_b16 v147, v155 offset:9520
	ds_write_b16_d16_hi v147, v155 offset:9656
	ds_write_b16 v147, v156 offset:17408
	ds_write_b16_d16_hi v147, v156 offset:17544
	ds_write_b16 v147, v157 offset:17680
	ds_write_b16_d16_hi v147, v157 offset:17816
	ds_write_b16 v147, v158 offset:17952
	ds_write_b16_d16_hi v147, v158 offset:18088
	ds_write_b16 v147, v159 offset:18224
	ds_write_b16_d16_hi v147, v159 offset:18360
	ds_write_b16 v147, v160 offset:26112
	ds_write_b16_d16_hi v147, v160 offset:26248
	ds_write_b16 v147, v161 offset:26384
	ds_write_b16_d16_hi v147, v161 offset:26520
	ds_write_b16 v147, v162 offset:26656
	ds_write_b16_d16_hi v147, v162 offset:26792
	ds_write_b16 v147, v163 offset:26928
	ds_write_b16_d16_hi v147, v163 offset:27064
	ds_write_b16 v147, v164 offset:34816
	ds_write_b16_d16_hi v147, v164 offset:34952
	ds_write_b16 v147, v165 offset:35088
	ds_write_b16_d16_hi v147, v165 offset:35224
	ds_write_b16 v147, v166 offset:35360
	ds_write_b16_d16_hi v147, v166 offset:35496
	ds_write_b16 v147, v167 offset:35632
	ds_write_b16_d16_hi v147, v167 offset:35768
	ds_write_b16 v147, v168 offset:43520
	ds_write_b16_d16_hi v147, v168 offset:43656
	ds_write_b16 v147, v169 offset:43792
	ds_write_b16_d16_hi v147, v169 offset:43928
	ds_write_b16 v147, v170 offset:44064
	ds_write_b16_d16_hi v147, v170 offset:44200
	ds_write_b16 v147, v171 offset:44336
	ds_write_b16_d16_hi v147, v171 offset:44472
	ds_write_b128 v206, v[172:175] offset:52224
	ds_write_b128 v206, v[176:179] offset:52352
	ds_write_b128 v206, v[180:183] offset:52480
	ds_write_b128 v206, v[184:187] offset:52608
	ds_write_b128 v206, v[188:191] offset:52736
	ds_write_b128 v206, v[208:211] offset:52864
